# P0 weight transposes: 16 loads per pass issued back to back as global loads with counted waits (was one flat load in flight per wave) (on v63)
# speedup vs baseline: 1.0147x; 1.0147x over previous
; #define LAS __attribute__((address_space(3)))
; __device__ __forceinline__ unsigned pk2(float lo, float hi) { f32x2 v = {lo, hi}; bf16x2_t b = __builtin_convertvector(v, bf16x2_t); return __builtin_bit_cast(unsigned, b); }
; __device__ __forceinline__ void tr_item(const float* W, int K, int N, bf16_t* WT, int ldt, int rowmode, const float* ksc, LAS float* scr, int item, int lane) {
;     const int nblk = N / 32, kb = item / nblk, nb = item % nblk, k0 = 64 * kb, n0 = 32 * nb;
; #pragma unroll 16
;     for (int i = 0; i < 32; ++i) { const int kk = 2 * i + (lane >> 5); float v = W[(size_t)(k0 + kk) * N + n0 + (lane & 31)]; if (ksc) v *= ksc[k0 + kk]; scr[kk * 33 + (lane & 31)] = v; }
;     asm volatile("s_waitcnt lgkmcnt(0)" ::: "memory");
;     const int c = lane & 7;
; #pragma unroll
;     for (int j = 0; j < 4; ++j) { const int n = n0 + (lane >> 3) + 8 * j; const LAS float* s = scr + (8 * c) * 33 + (lane >> 3) + 8 * j;
;         u32x4 o; o.x = pk2(s[0 * 33], s[1 * 33]); o.y = pk2(s[2 * 33], s[3 * 33]); o.z = pk2(s[4 * 33], s[5 * 33]); o.w = pk2(s[6 * 33], s[7 * 33]);
;         int row = n; if (rowmode) row = (n >> 7) * 256 + (n & 127) + (rowmode == 2 ? 128 : 0);
;         *(u32x4*)(WT + (size_t)row * ldt + k0 + 8 * c) = o; }
;     asm volatile("s_waitcnt lgkmcnt(0)" ::: "memory");
.LBB0_25:
	v_lshl_add_u64 v[38:39], v[34:35], 0, s[18:19]
	global_load_dword v100, v[38:39], off
	v_lshl_add_u64 v[38:39], v[32:33], 0, s[18:19]
	global_load_dword v101, v[38:39], off
	v_lshl_add_u64 v[38:39], v[30:31], 0, s[18:19]
	global_load_dword v102, v[38:39], off
	v_lshl_add_u64 v[38:39], v[28:29], 0, s[18:19]
	global_load_dword v103, v[38:39], off
	v_lshl_add_u64 v[38:39], v[26:27], 0, s[18:19]
	global_load_dword v104, v[38:39], off
	v_lshl_add_u64 v[38:39], v[24:25], 0, s[18:19]
	global_load_dword v105, v[38:39], off
	v_lshl_add_u64 v[38:39], v[22:23], 0, s[18:19]
	global_load_dword v106, v[38:39], off
	v_lshl_add_u64 v[38:39], v[20:21], 0, s[18:19]
	global_load_dword v107, v[38:39], off
	v_lshl_add_u64 v[38:39], v[18:19], 0, s[18:19]
	global_load_dword v108, v[38:39], off
	v_lshl_add_u64 v[38:39], v[16:17], 0, s[18:19]
	global_load_dword v109, v[38:39], off
	v_lshl_add_u64 v[38:39], v[14:15], 0, s[18:19]
	global_load_dword v110, v[38:39], off
	v_lshl_add_u64 v[38:39], v[12:13], 0, s[18:19]
	global_load_dword v111, v[38:39], off
	v_lshl_add_u64 v[38:39], v[10:11], 0, s[18:19]
	global_load_dword v112, v[38:39], off
	v_lshl_add_u64 v[38:39], v[8:9], 0, s[18:19]
	global_load_dword v113, v[38:39], off
	v_lshl_add_u64 v[38:39], v[6:7], 0, s[18:19]
	global_load_dword v114, v[38:39], off
	v_lshl_add_u64 v[38:39], v[4:5], 0, s[18:19]
	s_add_u32 s18, s18, 0x20000
	s_addc_u32 s19, s19, 0
	s_cmp_lg_u32 s18, 0x40000
	global_load_dword v115, v[38:39], off
	s_waitcnt vmcnt(15)
	ds_write_b32 v36, v100
	s_waitcnt vmcnt(14)
	ds_write_b32 v36, v101 offset:264
	s_waitcnt vmcnt(13)
	ds_write_b32 v36, v102 offset:528
	s_waitcnt vmcnt(12)
	ds_write_b32 v36, v103 offset:792
	s_waitcnt vmcnt(11)
	ds_write_b32 v36, v104 offset:1056
	s_waitcnt vmcnt(10)
	ds_write_b32 v36, v105 offset:1320
	s_waitcnt vmcnt(9)
	ds_write_b32 v36, v106 offset:1584
	s_waitcnt vmcnt(8)
	ds_write_b32 v36, v107 offset:1848
	s_waitcnt vmcnt(7)
	ds_write_b32 v36, v108 offset:2112
	s_waitcnt vmcnt(6)
	ds_write_b32 v36, v109 offset:2376
	s_waitcnt vmcnt(5)
	ds_write_b32 v36, v110 offset:2640
	s_waitcnt vmcnt(4)
	ds_write_b32 v36, v111 offset:2904
	s_waitcnt vmcnt(3)
	ds_write_b32 v36, v112 offset:3168
	s_waitcnt vmcnt(2)
	ds_write_b32 v36, v113 offset:3432
	s_waitcnt vmcnt(1)
	ds_write_b32 v36, v114 offset:3696
	s_waitcnt vmcnt(0)
	ds_write_b32 v36, v115 offset:3960
	v_add_u32_e32 v36, 0x1080, v36
	s_cbranch_scc1 .LBB0_25
	v_ashrrev_i32_e32 v4, 3, v2
	v_lshlrev_b32_e32 v2, 3, v2
	v_and_b32_e32 v2, 56, v2
	s_and_b64 s[4:5], s[4:5], exec
	v_add_u32_e32 v28, s10, v4
	v_mul_u32_u24_e32 v5, 0x84, v2
	v_lshlrev_b32_e32 v4, 2, v4
	s_cselect_b32 s4, 0x580000, 0
	s_waitcnt lgkmcnt(0)
	v_add3_u32 v29, s3, v5, v4
	s_add_u32 s11, s38, s4
	ds_read2_b32 v[8:9], v29 offset0:33 offset1:41
	ds_read2_b32 v[10:11], v29 offset1:8
	ds_read2_b32 v[12:13], v29 offset0:66 offset1:74
	ds_read2_b32 v[14:15], v29 offset0:99 offset1:107
	ds_read2_b32 v[16:17], v29 offset0:132 offset1:140
	ds_read2_b32 v[18:19], v29 offset0:165 offset1:173
	ds_read2_b32 v[20:21], v29 offset0:198 offset1:206
	ds_read2_b32 v[22:23], v29 offset0:231 offset1:239
	s_addc_u32 s14, s39, 0
	s_lshl_b64 s[4:5], s[8:9], 1
	s_add_u32 s4, s11, s4
	s_addc_u32 s5, s14, s5
	v_lshlrev_b32_e32 v2, 1, v2
	v_lshl_add_u64 v[24:25], s[4:5], 0, v[2:3]
	s_waitcnt lgkmcnt(6)
	v_cvt_pk_bf16_f32 v4, v10, v8
	s_waitcnt lgkmcnt(4)
	v_cvt_pk_bf16_f32 v5, v12, v14
	s_waitcnt lgkmcnt(2)
	v_cvt_pk_bf16_f32 v6, v16, v18
	s_waitcnt lgkmcnt(0)
	v_cvt_pk_bf16_f32 v7, v20, v22
	v_mad_i64_i32 v[26:27], s[4:5], v28, s56, v[24:25]
	v_add_u32_e32 v2, 8, v28
	global_store_dwordx4 v[26:27], v[4:7], off
	s_nop 1
	v_cvt_pk_bf16_f32 v4, v11, v9
	v_cvt_pk_bf16_f32 v5, v13, v15
	v_cvt_pk_bf16_f32 v6, v17, v19
	v_cvt_pk_bf16_f32 v7, v21, v23
	v_mad_i64_i32 v[8:9], s[4:5], v2, s56, v[24:25]
	global_store_dwordx4 v[8:9], v[4:7], off
	ds_read2_b32 v[8:9], v29 offset0:49 offset1:57
	ds_read2_b32 v[10:11], v29 offset0:16 offset1:24
	ds_read2_b32 v[12:13], v29 offset0:82 offset1:90
	ds_read2_b32 v[14:15], v29 offset0:115 offset1:123
	ds_read2_b32 v[16:17], v29 offset0:148 offset1:156
	ds_read2_b32 v[18:19], v29 offset0:181 offset1:189
	ds_read2_b32 v[20:21], v29 offset0:214 offset1:222
	ds_read2_b32 v[22:23], v29 offset0:247 offset1:255
	v_add_u32_e32 v2, 16, v28
	s_waitcnt lgkmcnt(6)
	v_cvt_pk_bf16_f32 v4, v10, v8
	s_waitcnt lgkmcnt(4)
	v_cvt_pk_bf16_f32 v5, v12, v14
	s_waitcnt lgkmcnt(2)
	v_cvt_pk_bf16_f32 v6, v16, v18
	s_waitcnt lgkmcnt(0)
	v_cvt_pk_bf16_f32 v7, v20, v22
	v_mad_i64_i32 v[26:27], s[4:5], v2, s56, v[24:25]
	v_add_u32_e32 v2, 24, v28
	global_store_dwordx4 v[26:27], v[4:7], off
	s_nop 1
	v_cvt_pk_bf16_f32 v4, v11, v9
	v_cvt_pk_bf16_f32 v5, v13, v15
	v_cvt_pk_bf16_f32 v6, v17, v19
	v_cvt_pk_bf16_f32 v7, v21, v23
	v_mad_i64_i32 v[8:9], s[4:5], v2, s56, v[24:25]
	global_store_dwordx4 v[8:9], v[4:7], off
	s_waitcnt lgkmcnt(0)
	s_mov_b64 s[4:5], 0

; #define LAS __attribute__((address_space(3)))
; __device__ __forceinline__ unsigned pk2(float lo, float hi) { f32x2 v = {lo, hi}; bf16x2_t b = __builtin_convertvector(v, bf16x2_t); return __builtin_bit_cast(unsigned, b); }
; __device__ __forceinline__ void tr_item(const float* W, int K, int N, bf16_t* WT, int ldt, int rowmode, const float* ksc, LAS float* scr, int item, int lane) {
;     const int nblk = N / 32, kb = item / nblk, nb = item % nblk, k0 = 64 * kb, n0 = 32 * nb;
; #pragma unroll 16
;     for (int i = 0; i < 32; ++i) { const int kk = 2 * i + (lane >> 5); float v = W[(size_t)(k0 + kk) * N + n0 + (lane & 31)]; if (ksc) v *= ksc[k0 + kk]; scr[kk * 33 + (lane & 31)] = v; }
;     asm volatile("s_waitcnt lgkmcnt(0)" ::: "memory");
;     const int c = lane & 7;
; #pragma unroll
;     for (int j = 0; j < 4; ++j) { const int n = n0 + (lane >> 3) + 8 * j; const LAS float* s = scr + (8 * c) * 33 + (lane >> 3) + 8 * j;
;         u32x4 o; o.x = pk2(s[0 * 33], s[1 * 33]); o.y = pk2(s[2 * 33], s[3 * 33]); o.z = pk2(s[4 * 33], s[5 * 33]); o.w = pk2(s[6 * 33], s[7 * 33]);
;         int row = n; if (rowmode) row = (n >> 7) * 256 + (n & 127) + (rowmode == 2 ? 128 : 0);
;         *(u32x4*)(WT + (size_t)row * ldt + k0 + 8 * c) = o; }
;     asm volatile("s_waitcnt lgkmcnt(0)" ::: "memory");
.LBB0_29:
	v_lshl_add_u64 v[38:39], v[34:35], 0, s[10:11]
	global_load_dword v100, v[38:39], off
	v_lshl_add_u64 v[38:39], v[32:33], 0, s[10:11]
	global_load_dword v101, v[38:39], off
	v_lshl_add_u64 v[38:39], v[30:31], 0, s[10:11]
	global_load_dword v102, v[38:39], off
	v_lshl_add_u64 v[38:39], v[28:29], 0, s[10:11]
	global_load_dword v103, v[38:39], off
	v_lshl_add_u64 v[38:39], v[26:27], 0, s[10:11]
	global_load_dword v104, v[38:39], off
	v_lshl_add_u64 v[38:39], v[24:25], 0, s[10:11]
	global_load_dword v105, v[38:39], off
	v_lshl_add_u64 v[38:39], v[22:23], 0, s[10:11]
	global_load_dword v106, v[38:39], off
	v_lshl_add_u64 v[38:39], v[20:21], 0, s[10:11]
	global_load_dword v107, v[38:39], off
	v_lshl_add_u64 v[38:39], v[18:19], 0, s[10:11]
	global_load_dword v108, v[38:39], off
	v_lshl_add_u64 v[38:39], v[16:17], 0, s[10:11]
	global_load_dword v109, v[38:39], off
	v_lshl_add_u64 v[38:39], v[14:15], 0, s[10:11]
	global_load_dword v110, v[38:39], off
	v_lshl_add_u64 v[38:39], v[12:13], 0, s[10:11]
	global_load_dword v111, v[38:39], off
	v_lshl_add_u64 v[38:39], v[10:11], 0, s[10:11]
	global_load_dword v112, v[38:39], off
	v_lshl_add_u64 v[38:39], v[8:9], 0, s[10:11]
	global_load_dword v113, v[38:39], off
	v_lshl_add_u64 v[38:39], v[6:7], 0, s[10:11]
	global_load_dword v114, v[38:39], off
	v_lshl_add_u64 v[38:39], v[4:5], 0, s[10:11]
	s_add_u32 s10, s10, 0x58000
	s_addc_u32 s11, s11, 0
	s_cmp_lg_u32 s10, 0xb0000
	global_load_dword v115, v[38:39], off
	s_waitcnt vmcnt(15)
	ds_write_b32 v36, v100
	s_waitcnt vmcnt(14)
	ds_write_b32 v36, v101 offset:264
	s_waitcnt vmcnt(13)
	ds_write_b32 v36, v102 offset:528
	s_waitcnt vmcnt(12)
	ds_write_b32 v36, v103 offset:792
	s_waitcnt vmcnt(11)
	ds_write_b32 v36, v104 offset:1056
	s_waitcnt vmcnt(10)
	ds_write_b32 v36, v105 offset:1320
	s_waitcnt vmcnt(9)
	ds_write_b32 v36, v106 offset:1584
	s_waitcnt vmcnt(8)
	ds_write_b32 v36, v107 offset:1848
	s_waitcnt vmcnt(7)
	ds_write_b32 v36, v108 offset:2112
	s_waitcnt vmcnt(6)
	ds_write_b32 v36, v109 offset:2376
	s_waitcnt vmcnt(5)
	ds_write_b32 v36, v110 offset:2640
	s_waitcnt vmcnt(4)
	ds_write_b32 v36, v111 offset:2904
	s_waitcnt vmcnt(3)
	ds_write_b32 v36, v112 offset:3168
	s_waitcnt vmcnt(2)
	ds_write_b32 v36, v113 offset:3432
	s_waitcnt vmcnt(1)
	ds_write_b32 v36, v114 offset:3696
	s_waitcnt vmcnt(0)
	ds_write_b32 v36, v115 offset:3960
	v_add_u32_e32 v36, 0x1080, v36
	s_cbranch_scc1 .LBB0_29
	s_lshr_b32 s9, s18, 1
	s_mul_i32 s9, s9, 0xb00000
	s_add_u32 s9, s36, s9
	v_ashrrev_i32_e32 v4, 3, v2
	v_lshlrev_b32_e32 v2, 3, v2
	s_addc_u32 s10, s37, 0
	v_add_u32_e32 v28, s8, v4
	v_and_b32_e32 v2, 56, v2
	s_lshl_b32 s8, s14, 7
	s_lshl_b64 s[4:5], s[4:5], 1
	v_mul_u32_u24_e32 v5, 0x84, v2
	v_lshlrev_b32_e32 v4, 2, v4
	s_add_u32 s4, s9, s4
	s_waitcnt lgkmcnt(0)
	v_add3_u32 v29, s3, v5, v4
	s_addc_u32 s5, s10, s5
	v_lshlrev_b32_e32 v2, 1, v2
	ds_read2_b32 v[8:9], v29 offset0:33 offset1:41
	ds_read2_b32 v[10:11], v29 offset1:8
	ds_read2_b32 v[12:13], v29 offset0:66 offset1:74
	ds_read2_b32 v[14:15], v29 offset0:99 offset1:107
	ds_read2_b32 v[16:17], v29 offset0:132 offset1:140
	ds_read2_b32 v[18:19], v29 offset0:165 offset1:173
	ds_read2_b32 v[20:21], v29 offset0:198 offset1:206
	ds_read2_b32 v[22:23], v29 offset0:231 offset1:239
	v_lshl_add_u64 v[24:25], s[4:5], 0, v[2:3]
	v_lshlrev_b32_e32 v2, 1, v28
	s_waitcnt lgkmcnt(6)
	v_cvt_pk_bf16_f32 v4, v10, v8
	v_and_b32_e32 v2, 0xffffff00, v2
	v_and_b32_e32 v8, 0x7f, v28
	v_or3_b32 v26, v8, v2, s8
	v_add_u32_e32 v2, 8, v28
	v_ashrrev_i32_e32 v27, 31, v26
	v_lshlrev_b32_e32 v8, 1, v2
	v_lshlrev_b64 v[26:27], 11, v[26:27]
	v_and_b32_e32 v8, 0xffffff00, v8
	v_and_b32_e32 v2, 0x7f, v2
	s_waitcnt lgkmcnt(4)
	v_cvt_pk_bf16_f32 v5, v12, v14
	s_waitcnt lgkmcnt(2)
	v_cvt_pk_bf16_f32 v6, v16, v18
	s_waitcnt lgkmcnt(0)
	v_cvt_pk_bf16_f32 v7, v20, v22
	v_lshl_add_u64 v[26:27], v[24:25], 0, v[26:27]
	v_or3_b32 v8, v2, v8, s8
	global_store_dwordx4 v[26:27], v[4:7], off
	v_add_u32_e32 v2, 16, v28
	s_nop 0
	v_cvt_pk_bf16_f32 v4, v11, v9
	v_ashrrev_i32_e32 v9, 31, v8
	v_lshlrev_b64 v[8:9], 11, v[8:9]
	v_cvt_pk_bf16_f32 v5, v13, v15
	v_cvt_pk_bf16_f32 v6, v17, v19
	v_cvt_pk_bf16_f32 v7, v21, v23
	v_lshl_add_u64 v[8:9], v[24:25], 0, v[8:9]
	global_store_dwordx4 v[8:9], v[4:7], off
	ds_read2_b32 v[8:9], v29 offset0:16 offset1:24
	ds_read2_b32 v[10:11], v29 offset0:49 offset1:57
	ds_read2_b32 v[12:13], v29 offset0:82 offset1:90
	ds_read2_b32 v[14:15], v29 offset0:115 offset1:123
	ds_read2_b32 v[16:17], v29 offset0:148 offset1:156
	ds_read2_b32 v[18:19], v29 offset0:181 offset1:189
	ds_read2_b32 v[20:21], v29 offset0:214 offset1:222
	ds_read2_b32 v[22:23], v29 offset0:247 offset1:255
	s_waitcnt lgkmcnt(6)
	v_cvt_pk_bf16_f32 v4, v8, v10
	v_lshlrev_b32_e32 v8, 1, v2
	v_and_b32_e32 v8, 0xffffff00, v8
	v_and_b32_e32 v2, 0x7f, v2
	v_or3_b32 v26, v2, v8, s8
	v_add_u32_e32 v2, 24, v28
	v_ashrrev_i32_e32 v27, 31, v26
	v_lshlrev_b32_e32 v8, 1, v2
	v_lshlrev_b64 v[26:27], 11, v[26:27]
	v_and_b32_e32 v8, 0xffffff00, v8
	v_and_b32_e32 v2, 0x7f, v2
	s_waitcnt lgkmcnt(4)
	v_cvt_pk_bf16_f32 v5, v12, v14
	s_waitcnt lgkmcnt(2)
	v_cvt_pk_bf16_f32 v6, v16, v18
	s_waitcnt lgkmcnt(0)
	v_cvt_pk_bf16_f32 v7, v20, v22
	v_lshl_add_u64 v[26:27], v[24:25], 0, v[26:27]
	v_or3_b32 v8, v2, v8, s8
	global_store_dwordx4 v[26:27], v[4:7], off
	s_nop 1
	v_cvt_pk_bf16_f32 v4, v9, v11
	v_ashrrev_i32_e32 v9, 31, v8
	v_lshlrev_b64 v[8:9], 11, v[8:9]
	v_cvt_pk_bf16_f32 v5, v13, v15
	v_cvt_pk_bf16_f32 v6, v17, v19
	v_cvt_pk_bf16_f32 v7, v21, v23
	v_lshl_add_u64 v[8:9], v[24:25], 0, v[8:9]
	global_store_dwordx4 v[8:9], v[4:7], off
	s_waitcnt lgkmcnt(0)

; #define LAS __attribute__((address_space(3)))
; __device__ __forceinline__ unsigned pk2(float lo, float hi) { f32x2 v = {lo, hi}; bf16x2_t b = __builtin_convertvector(v, bf16x2_t); return __builtin_bit_cast(unsigned, b); }
; __device__ __forceinline__ void tr_item(const float* W, int K, int N, bf16_t* WT, int ldt, int rowmode, const float* ksc, LAS float* scr, int item, int lane) {
;     const int nblk = N / 32, kb = item / nblk, nb = item % nblk, k0 = 64 * kb, n0 = 32 * nb;
; #pragma unroll 16
;     for (int i = 0; i < 32; ++i) { const int kk = 2 * i + (lane >> 5); float v = W[(size_t)(k0 + kk) * N + n0 + (lane & 31)]; if (ksc) v *= ksc[k0 + kk]; scr[kk * 33 + (lane & 31)] = v; }
;     asm volatile("s_waitcnt lgkmcnt(0)" ::: "memory");
;     const int c = lane & 7;
; #pragma unroll
;     for (int j = 0; j < 4; ++j) { const int n = n0 + (lane >> 3) + 8 * j; const LAS float* s = scr + (8 * c) * 33 + (lane >> 3) + 8 * j;
;         u32x4 o; o.x = pk2(s[0 * 33], s[1 * 33]); o.y = pk2(s[2 * 33], s[3 * 33]); o.z = pk2(s[4 * 33], s[5 * 33]); o.w = pk2(s[6 * 33], s[7 * 33]);
;         int row = n; if (rowmode) row = (n >> 7) * 256 + (n & 127) + (rowmode == 2 ? 128 : 0);
;         *(u32x4*)(WT + (size_t)row * ldt + k0 + 8 * c) = o; }
;     asm volatile("s_waitcnt lgkmcnt(0)" ::: "memory");
.LBB0_34:
	v_lshl_add_u64 v[38:39], v[34:35], 0, s[4:5]
	global_load_dword v100, v[38:39], off
	v_lshl_add_u64 v[38:39], v[32:33], 0, s[4:5]
	global_load_dword v101, v[38:39], off
	v_lshl_add_u64 v[38:39], v[30:31], 0, s[4:5]
	global_load_dword v102, v[38:39], off
	v_lshl_add_u64 v[38:39], v[28:29], 0, s[4:5]
	global_load_dword v103, v[38:39], off
	v_lshl_add_u64 v[38:39], v[26:27], 0, s[4:5]
	global_load_dword v104, v[38:39], off
	v_lshl_add_u64 v[38:39], v[24:25], 0, s[4:5]
	global_load_dword v105, v[38:39], off
	v_lshl_add_u64 v[38:39], v[22:23], 0, s[4:5]
	global_load_dword v106, v[38:39], off
	v_lshl_add_u64 v[38:39], v[20:21], 0, s[4:5]
	global_load_dword v107, v[38:39], off
	v_lshl_add_u64 v[38:39], v[18:19], 0, s[4:5]
	global_load_dword v108, v[38:39], off
	v_lshl_add_u64 v[38:39], v[16:17], 0, s[4:5]
	global_load_dword v109, v[38:39], off
	v_lshl_add_u64 v[38:39], v[14:15], 0, s[4:5]
	global_load_dword v110, v[38:39], off
	v_lshl_add_u64 v[38:39], v[12:13], 0, s[4:5]
	global_load_dword v111, v[38:39], off
	v_lshl_add_u64 v[38:39], v[10:11], 0, s[4:5]
	global_load_dword v112, v[38:39], off
	v_lshl_add_u64 v[38:39], v[8:9], 0, s[4:5]
	global_load_dword v113, v[38:39], off
	v_lshl_add_u64 v[38:39], v[6:7], 0, s[4:5]
	global_load_dword v114, v[38:39], off
	v_lshl_add_u64 v[38:39], v[4:5], 0, s[4:5]
	s_add_u32 s4, s4, 0x20000
	s_addc_u32 s5, s5, 0
	s_cmp_lg_u32 s4, 0x40000
	global_load_dword v115, v[38:39], off
	s_waitcnt vmcnt(15)
	ds_write_b32 v37, v100
	s_waitcnt vmcnt(14)
	ds_write_b32 v37, v101 offset:264
	s_waitcnt vmcnt(13)
	ds_write_b32 v37, v102 offset:528
	s_waitcnt vmcnt(12)
	ds_write_b32 v37, v103 offset:792
	s_waitcnt vmcnt(11)
	ds_write_b32 v37, v104 offset:1056
	s_waitcnt vmcnt(10)
	ds_write_b32 v37, v105 offset:1320
	s_waitcnt vmcnt(9)
	ds_write_b32 v37, v106 offset:1584
	s_waitcnt vmcnt(8)
	ds_write_b32 v37, v107 offset:1848
	s_waitcnt vmcnt(7)
	ds_write_b32 v37, v108 offset:2112
	s_waitcnt vmcnt(6)
	ds_write_b32 v37, v109 offset:2376
	s_waitcnt vmcnt(5)
	ds_write_b32 v37, v110 offset:2640
	s_waitcnt vmcnt(4)
	ds_write_b32 v37, v111 offset:2904
	s_waitcnt vmcnt(3)
	ds_write_b32 v37, v112 offset:3168
	s_waitcnt vmcnt(2)
	ds_write_b32 v37, v113 offset:3432
	s_waitcnt vmcnt(1)
	ds_write_b32 v37, v114 offset:3696
	s_waitcnt vmcnt(0)
	ds_write_b32 v37, v115 offset:3960
	v_add_u32_e32 v37, 0x1080, v37
	s_cbranch_scc1 .LBB0_34
	s_lshl_b32 s5, s1, 5
	v_lshlrev_b32_e32 v4, 3, v36
	s_and_b32 s5, s5, 0x3e0
	v_ashrrev_i32_e32 v2, 3, v36
	v_and_b32_e32 v4, 56, v4
	s_lshl_b32 s4, s1, 1
	v_add_u32_e32 v8, s5, v2
	v_mul_u32_u24_e32 v5, 0x84, v4
	v_lshlrev_b32_e32 v2, 2, v2
	s_add_i32 s4, s4, 0x1e040
	s_waitcnt lgkmcnt(0)
	v_add3_u32 v28, s3, v5, v2
	s_and_b32 s4, s4, 0x1ffc0
	ds_read2_b32 v[10:11], v28 offset0:33 offset1:41
	ds_read2_b32 v[12:13], v28 offset1:8
	ds_read2_b32 v[14:15], v28 offset0:66 offset1:74
	ds_read2_b32 v[16:17], v28 offset0:99 offset1:107
	ds_read2_b32 v[18:19], v28 offset0:132 offset1:140
	ds_read2_b32 v[20:21], v28 offset0:165 offset1:173
	ds_read2_b32 v[22:23], v28 offset0:198 offset1:206
	ds_read2_b32 v[24:25], v28 offset0:231 offset1:239
	s_lshl_b32 s4, s4, 1
	s_add_u32 s4, s34, s4
	s_addc_u32 s5, s35, 0
	v_lshlrev_b32_e32 v2, 1, v4
	v_ashrrev_i32_e32 v9, 31, v8
	v_lshl_add_u64 v[26:27], s[4:5], 0, v[2:3]
	v_lshlrev_b64 v[8:9], 11, v[8:9]
	s_waitcnt lgkmcnt(6)
	v_cvt_pk_bf16_f32 v4, v12, v10
	s_waitcnt lgkmcnt(4)
	v_cvt_pk_bf16_f32 v5, v14, v16
	s_waitcnt lgkmcnt(2)
	v_cvt_pk_bf16_f32 v6, v18, v20
	s_waitcnt lgkmcnt(0)
	v_cvt_pk_bf16_f32 v7, v22, v24
	v_lshl_add_u64 v[8:9], v[26:27], 0, v[8:9]
	global_store_dwordx4 v[8:9], v[4:7], off
	v_add_co_u32_e32 v10, vcc, s59, v8
	s_nop 0
	v_cvt_pk_bf16_f32 v4, v13, v11
	v_cvt_pk_bf16_f32 v5, v15, v17
	v_cvt_pk_bf16_f32 v6, v19, v21
	v_cvt_pk_bf16_f32 v7, v23, v25
	ds_read2_b32 v[12:13], v28 offset0:49 offset1:57
	ds_read2_b32 v[14:15], v28 offset0:16 offset1:24
	ds_read2_b32 v[16:17], v28 offset0:82 offset1:90
	ds_read2_b32 v[18:19], v28 offset0:115 offset1:123
	ds_read2_b32 v[20:21], v28 offset0:148 offset1:156
	ds_read2_b32 v[22:23], v28 offset0:181 offset1:189
	ds_read2_b32 v[24:25], v28 offset0:214 offset1:222
	ds_read2_b32 v[26:27], v28 offset0:247 offset1:255
	v_addc_co_u32_e32 v11, vcc, 0, v9, vcc
	global_store_dwordx4 v[10:11], v[4:7], off
	v_add_co_u32_e32 v10, vcc, s60, v8
	s_waitcnt lgkmcnt(6)
	v_cvt_pk_bf16_f32 v4, v14, v12
	v_addc_co_u32_e32 v11, vcc, 0, v9, vcc
	s_waitcnt lgkmcnt(4)
	v_cvt_pk_bf16_f32 v5, v16, v18
	s_waitcnt lgkmcnt(2)
	v_cvt_pk_bf16_f32 v6, v20, v22
	s_waitcnt lgkmcnt(0)
	v_cvt_pk_bf16_f32 v7, v24, v26
	v_add_co_u32_e32 v8, vcc, 0xc000, v8
	global_store_dwordx4 v[10:11], v[4:7], off
	s_nop 0
	v_addc_co_u32_e32 v9, vcc, 0, v9, vcc
	v_cvt_pk_bf16_f32 v4, v15, v13
	v_cvt_pk_bf16_f32 v5, v17, v19
	v_cvt_pk_bf16_f32 v6, v21, v23
	v_cvt_pk_bf16_f32 v7, v25, v27
	global_store_dwordx4 v[8:9], v[4:7], off
	s_waitcnt lgkmcnt(0)

; #define LAS __attribute__((address_space(3)))
; __device__ __forceinline__ unsigned pk2(float lo, float hi) { f32x2 v = {lo, hi}; bf16x2_t b = __builtin_convertvector(v, bf16x2_t); return __builtin_bit_cast(unsigned, b); }
; __device__ __forceinline__ void tr_item(const float* W, int K, int N, bf16_t* WT, int ldt, int rowmode, const float* ksc, LAS float* scr, int item, int lane) {
;     const int nblk = N / 32, kb = item / nblk, nb = item % nblk, k0 = 64 * kb, n0 = 32 * nb;
; #pragma unroll 16
;     for (int i = 0; i < 32; ++i) { const int kk = 2 * i + (lane >> 5); float v = W[(size_t)(k0 + kk) * N + n0 + (lane & 31)]; if (ksc) v *= ksc[k0 + kk]; scr[kk * 33 + (lane & 31)] = v; }
;     asm volatile("s_waitcnt lgkmcnt(0)" ::: "memory");
;     const int c = lane & 7;
; #pragma unroll
;     for (int j = 0; j < 4; ++j) { const int n = n0 + (lane >> 3) + 8 * j; const LAS float* s = scr + (8 * c) * 33 + (lane >> 3) + 8 * j;
;         u32x4 o; o.x = pk2(s[0 * 33], s[1 * 33]); o.y = pk2(s[2 * 33], s[3 * 33]); o.z = pk2(s[4 * 33], s[5 * 33]); o.w = pk2(s[6 * 33], s[7 * 33]);
;         int row = n; if (rowmode) row = (n >> 7) * 256 + (n & 127) + (rowmode == 2 ? 128 : 0);
;         *(u32x4*)(WT + (size_t)row * ldt + k0 + 8 * c) = o; }
;     asm volatile("s_waitcnt lgkmcnt(0)" ::: "memory");
.LBB0_39:
	v_lshl_add_u64 v[38:39], v[34:35], 0, s[4:5]
	global_load_dword v100, v[38:39], off
	v_lshl_add_u64 v[38:39], v[32:33], 0, s[4:5]
	global_load_dword v101, v[38:39], off
	v_lshl_add_u64 v[38:39], v[30:31], 0, s[4:5]
	global_load_dword v102, v[38:39], off
	v_lshl_add_u64 v[38:39], v[28:29], 0, s[4:5]
	global_load_dword v103, v[38:39], off
	v_lshl_add_u64 v[38:39], v[26:27], 0, s[4:5]
	global_load_dword v104, v[38:39], off
	v_lshl_add_u64 v[38:39], v[24:25], 0, s[4:5]
	global_load_dword v105, v[38:39], off
	v_lshl_add_u64 v[38:39], v[22:23], 0, s[4:5]
	global_load_dword v106, v[38:39], off
	v_lshl_add_u64 v[38:39], v[20:21], 0, s[4:5]
	global_load_dword v107, v[38:39], off
	v_lshl_add_u64 v[38:39], v[18:19], 0, s[4:5]
	global_load_dword v108, v[38:39], off
	v_lshl_add_u64 v[38:39], v[16:17], 0, s[4:5]
	global_load_dword v109, v[38:39], off
	v_lshl_add_u64 v[38:39], v[14:15], 0, s[4:5]
	global_load_dword v110, v[38:39], off
	v_lshl_add_u64 v[38:39], v[12:13], 0, s[4:5]
	global_load_dword v111, v[38:39], off
	v_lshl_add_u64 v[38:39], v[10:11], 0, s[4:5]
	global_load_dword v112, v[38:39], off
	v_lshl_add_u64 v[38:39], v[8:9], 0, s[4:5]
	global_load_dword v113, v[38:39], off
	v_lshl_add_u64 v[38:39], v[6:7], 0, s[4:5]
	global_load_dword v114, v[38:39], off
	v_lshl_add_u64 v[38:39], v[4:5], 0, s[4:5]
	s_add_u32 s4, s4, 0x80000
	s_addc_u32 s5, s5, 0
	s_cmp_lg_u32 s4, 0x100000
	global_load_dword v115, v[38:39], off
	s_waitcnt vmcnt(15)
	ds_write_b32 v36, v100
	s_waitcnt vmcnt(14)
	ds_write_b32 v36, v101 offset:264
	s_waitcnt vmcnt(13)
	ds_write_b32 v36, v102 offset:528
	s_waitcnt vmcnt(12)
	ds_write_b32 v36, v103 offset:792
	s_waitcnt vmcnt(11)
	ds_write_b32 v36, v104 offset:1056
	s_waitcnt vmcnt(10)
	ds_write_b32 v36, v105 offset:1320
	s_waitcnt vmcnt(9)
	ds_write_b32 v36, v106 offset:1584
	s_waitcnt vmcnt(8)
	ds_write_b32 v36, v107 offset:1848
	s_waitcnt vmcnt(7)
	ds_write_b32 v36, v108 offset:2112
	s_waitcnt vmcnt(6)
	ds_write_b32 v36, v109 offset:2376
	s_waitcnt vmcnt(5)
	ds_write_b32 v36, v110 offset:2640
	s_waitcnt vmcnt(4)
	ds_write_b32 v36, v111 offset:2904
	s_waitcnt vmcnt(3)
	ds_write_b32 v36, v112 offset:3168
	s_waitcnt vmcnt(2)
	ds_write_b32 v36, v113 offset:3432
	s_waitcnt vmcnt(1)
	ds_write_b32 v36, v114 offset:3696
	s_waitcnt vmcnt(0)
	ds_write_b32 v36, v115 offset:3960
	v_add_u32_e32 v36, 0x1080, v36
	s_cbranch_scc1 .LBB0_39
	s_add_i32 s4, s1, 0xfffff820
	s_lshl_b32 s5, s4, 5
	v_ashrrev_i32_e32 v4, 3, v2
	v_lshlrev_b32_e32 v2, 3, v2
	s_and_b32 s5, s5, 0xfe0
	v_and_b32_e32 v2, 56, v2
	v_add_u32_e32 v8, s5, v4
	v_mul_u32_u24_e32 v5, 0x84, v2
	v_lshlrev_b32_e32 v4, 2, v4
	s_waitcnt lgkmcnt(0)
	v_add3_u32 v28, s3, v5, v4
	ds_read2_b32 v[10:11], v28 offset0:33 offset1:41
	ds_read2_b32 v[12:13], v28 offset1:8
	ds_read2_b32 v[14:15], v28 offset0:66 offset1:74
	ds_read2_b32 v[16:17], v28 offset0:99 offset1:107
	ds_read2_b32 v[18:19], v28 offset0:132 offset1:140
	ds_read2_b32 v[20:21], v28 offset0:165 offset1:173
	ds_read2_b32 v[22:23], v28 offset0:198 offset1:206
	ds_read2_b32 v[24:25], v28 offset0:231 offset1:239
	s_and_b32 s4, s4, 0xff80
	s_add_u32 s4, s31, s4
	s_addc_u32 s5, s33, 0
	v_lshlrev_b32_e32 v2, 1, v2
	v_ashrrev_i32_e32 v9, 31, v8
	v_lshl_add_u64 v[26:27], s[4:5], 0, v[2:3]
	v_lshlrev_b64 v[8:9], 11, v[8:9]
	s_waitcnt lgkmcnt(6)
	v_cvt_pk_bf16_f32 v4, v12, v10
	s_waitcnt lgkmcnt(4)
	v_cvt_pk_bf16_f32 v5, v14, v16
	s_waitcnt lgkmcnt(2)
	v_cvt_pk_bf16_f32 v6, v18, v20
	s_waitcnt lgkmcnt(0)
	v_cvt_pk_bf16_f32 v7, v22, v24
	v_lshl_add_u64 v[8:9], v[26:27], 0, v[8:9]
	global_store_dwordx4 v[8:9], v[4:7], off
	v_add_co_u32_e32 v10, vcc, s59, v8
	s_nop 0
	v_cvt_pk_bf16_f32 v4, v13, v11
	v_cvt_pk_bf16_f32 v5, v15, v17
	v_cvt_pk_bf16_f32 v6, v19, v21
	v_cvt_pk_bf16_f32 v7, v23, v25
	ds_read2_b32 v[12:13], v28 offset0:49 offset1:57
	ds_read2_b32 v[14:15], v28 offset0:16 offset1:24
	ds_read2_b32 v[16:17], v28 offset0:82 offset1:90
	ds_read2_b32 v[18:19], v28 offset0:115 offset1:123
	ds_read2_b32 v[20:21], v28 offset0:148 offset1:156
	ds_read2_b32 v[22:23], v28 offset0:181 offset1:189
	ds_read2_b32 v[24:25], v28 offset0:214 offset1:222
	ds_read2_b32 v[26:27], v28 offset0:247 offset1:255
	v_addc_co_u32_e32 v11, vcc, 0, v9, vcc
	global_store_dwordx4 v[10:11], v[4:7], off
	v_add_co_u32_e32 v10, vcc, s60, v8
	s_waitcnt lgkmcnt(6)
	v_cvt_pk_bf16_f32 v4, v14, v12
	v_addc_co_u32_e32 v11, vcc, 0, v9, vcc
	s_waitcnt lgkmcnt(4)
	v_cvt_pk_bf16_f32 v5, v16, v18
	s_waitcnt lgkmcnt(2)
	v_cvt_pk_bf16_f32 v6, v20, v22
	s_waitcnt lgkmcnt(0)
	v_cvt_pk_bf16_f32 v7, v24, v26
	v_add_co_u32_e32 v8, vcc, 0xc000, v8
	global_store_dwordx4 v[10:11], v[4:7], off
	s_nop 0
	v_addc_co_u32_e32 v9, vcc, 0, v9, vcc
	v_cvt_pk_bf16_f32 v4, v15, v13
	v_cvt_pk_bf16_f32 v5, v17, v19
	v_cvt_pk_bf16_f32 v6, v21, v23
	v_cvt_pk_bf16_f32 v7, v25, v27
	global_store_dwordx4 v[8:9], v[4:7], off
	s_waitcnt lgkmcnt(0)

; #define LAS __attribute__((address_space(3)))
; __device__ __forceinline__ unsigned pk2(float lo, float hi) { f32x2 v = {lo, hi}; bf16x2_t b = __builtin_convertvector(v, bf16x2_t); return __builtin_bit_cast(unsigned, b); }
; __device__ __forceinline__ void tr_item(const float* W, int K, int N, bf16_t* WT, int ldt, int rowmode, const float* ksc, LAS float* scr, int item, int lane) {
;     const int nblk = N / 32, kb = item / nblk, nb = item % nblk, k0 = 64 * kb, n0 = 32 * nb;
; #pragma unroll 16
;     for (int i = 0; i < 32; ++i) { const int kk = 2 * i + (lane >> 5); float v = W[(size_t)(k0 + kk) * N + n0 + (lane & 31)]; if (ksc) v *= ksc[k0 + kk]; scr[kk * 33 + (lane & 31)] = v; }
;     asm volatile("s_waitcnt lgkmcnt(0)" ::: "memory");
;     const int c = lane & 7;
; #pragma unroll
;     for (int j = 0; j < 4; ++j) { const int n = n0 + (lane >> 3) + 8 * j; const LAS float* s = scr + (8 * c) * 33 + (lane >> 3) + 8 * j;
;         u32x4 o; o.x = pk2(s[0 * 33], s[1 * 33]); o.y = pk2(s[2 * 33], s[3 * 33]); o.z = pk2(s[4 * 33], s[5 * 33]); o.w = pk2(s[6 * 33], s[7 * 33]);
;         int row = n; if (rowmode) row = (n >> 7) * 256 + (n & 127) + (rowmode == 2 ? 128 : 0);
;         *(u32x4*)(WT + (size_t)row * ldt + k0 + 8 * c) = o; }
;     asm volatile("s_waitcnt lgkmcnt(0)" ::: "memory");
.LBB0_44:
	v_lshl_add_u64 v[38:39], v[34:35], 0, s[4:5]
	global_load_dword v100, v[38:39], off
	v_lshl_add_u64 v[38:39], v[32:33], 0, s[4:5]
	global_load_dword v101, v[38:39], off
	v_lshl_add_u64 v[38:39], v[30:31], 0, s[4:5]
	global_load_dword v102, v[38:39], off
	v_lshl_add_u64 v[38:39], v[28:29], 0, s[4:5]
	global_load_dword v103, v[38:39], off
	v_lshl_add_u64 v[38:39], v[26:27], 0, s[4:5]
	global_load_dword v104, v[38:39], off
	v_lshl_add_u64 v[38:39], v[24:25], 0, s[4:5]
	global_load_dword v105, v[38:39], off
	v_lshl_add_u64 v[38:39], v[22:23], 0, s[4:5]
	global_load_dword v106, v[38:39], off
	v_lshl_add_u64 v[38:39], v[20:21], 0, s[4:5]
	global_load_dword v107, v[38:39], off
	v_lshl_add_u64 v[38:39], v[18:19], 0, s[4:5]
	global_load_dword v108, v[38:39], off
	v_lshl_add_u64 v[38:39], v[16:17], 0, s[4:5]
	global_load_dword v109, v[38:39], off
	v_lshl_add_u64 v[38:39], v[14:15], 0, s[4:5]
	global_load_dword v110, v[38:39], off
	v_lshl_add_u64 v[38:39], v[12:13], 0, s[4:5]
	global_load_dword v111, v[38:39], off
	v_lshl_add_u64 v[38:39], v[10:11], 0, s[4:5]
	global_load_dword v112, v[38:39], off
	v_lshl_add_u64 v[38:39], v[8:9], 0, s[4:5]
	global_load_dword v113, v[38:39], off
	v_lshl_add_u64 v[38:39], v[6:7], 0, s[4:5]
	global_load_dword v114, v[38:39], off
	v_lshl_add_u64 v[38:39], v[4:5], 0, s[4:5]
	s_add_u32 s4, s4, 0x20000
	s_addc_u32 s5, s5, 0
	s_cmp_lg_u32 s4, 0x40000
	global_load_dword v115, v[38:39], off
	s_waitcnt vmcnt(15)
	ds_write_b32 v37, v100
	s_waitcnt vmcnt(14)
	ds_write_b32 v37, v101 offset:264
	s_waitcnt vmcnt(13)
	ds_write_b32 v37, v102 offset:528
	s_waitcnt vmcnt(12)
	ds_write_b32 v37, v103 offset:792
	s_waitcnt vmcnt(11)
	ds_write_b32 v37, v104 offset:1056
	s_waitcnt vmcnt(10)
	ds_write_b32 v37, v105 offset:1320
	s_waitcnt vmcnt(9)
	ds_write_b32 v37, v106 offset:1584
	s_waitcnt vmcnt(8)
	ds_write_b32 v37, v107 offset:1848
	s_waitcnt vmcnt(7)
	ds_write_b32 v37, v108 offset:2112
	s_waitcnt vmcnt(6)
	ds_write_b32 v37, v109 offset:2376
	s_waitcnt vmcnt(5)
	ds_write_b32 v37, v110 offset:2640
	s_waitcnt vmcnt(4)
	ds_write_b32 v37, v111 offset:2904
	s_waitcnt vmcnt(3)
	ds_write_b32 v37, v112 offset:3168
	s_waitcnt vmcnt(2)
	ds_write_b32 v37, v113 offset:3432
	s_waitcnt vmcnt(1)
	ds_write_b32 v37, v114 offset:3696
	s_waitcnt vmcnt(0)
	ds_write_b32 v37, v115 offset:3960
	v_add_u32_e32 v37, 0x1080, v37
	s_cbranch_scc1 .LBB0_44
	s_lshl_b32 s5, s1, 5
	v_lshlrev_b32_e32 v4, 3, v36
	s_and_b32 s5, s5, 0x3e0
	v_ashrrev_i32_e32 v2, 3, v36
	v_and_b32_e32 v4, 56, v4
	s_lshl_b32 s4, s1, 1
	v_add_u32_e32 v8, s5, v2
	v_mul_u32_u24_e32 v5, 0x84, v4
	v_lshlrev_b32_e32 v2, 2, v2
	s_add_i32 s4, s4, 0x1f440
	s_waitcnt lgkmcnt(0)
	v_add3_u32 v28, s3, v5, v2
	s_and_b32 s4, s4, 0x1ffc0
	ds_read2_b32 v[10:11], v28 offset0:33 offset1:41
	ds_read2_b32 v[12:13], v28 offset1:8
	ds_read2_b32 v[14:15], v28 offset0:66 offset1:74
	ds_read2_b32 v[16:17], v28 offset0:99 offset1:107
	ds_read2_b32 v[18:19], v28 offset0:132 offset1:140
	ds_read2_b32 v[20:21], v28 offset0:165 offset1:173
	ds_read2_b32 v[22:23], v28 offset0:198 offset1:206
	ds_read2_b32 v[24:25], v28 offset0:231 offset1:239
	s_lshl_b32 s4, s4, 1
	s_add_u32 s4, s29, s4
	s_addc_u32 s5, s30, 0
	v_lshlrev_b32_e32 v2, 1, v4
	v_ashrrev_i32_e32 v9, 31, v8
	v_lshl_add_u64 v[26:27], s[4:5], 0, v[2:3]
	v_lshlrev_b64 v[8:9], 11, v[8:9]
	s_waitcnt lgkmcnt(6)
	v_cvt_pk_bf16_f32 v4, v12, v10
	s_waitcnt lgkmcnt(4)
	v_cvt_pk_bf16_f32 v5, v14, v16
	s_waitcnt lgkmcnt(2)
	v_cvt_pk_bf16_f32 v6, v18, v20
	s_waitcnt lgkmcnt(0)
	v_cvt_pk_bf16_f32 v7, v22, v24
	v_lshl_add_u64 v[8:9], v[26:27], 0, v[8:9]
	global_store_dwordx4 v[8:9], v[4:7], off
	v_add_co_u32_e32 v10, vcc, s59, v8
	s_nop 0
	v_cvt_pk_bf16_f32 v4, v13, v11
	v_cvt_pk_bf16_f32 v5, v15, v17
	v_cvt_pk_bf16_f32 v6, v19, v21
	v_cvt_pk_bf16_f32 v7, v23, v25
	ds_read2_b32 v[12:13], v28 offset0:49 offset1:57
	ds_read2_b32 v[14:15], v28 offset0:16 offset1:24
	ds_read2_b32 v[16:17], v28 offset0:82 offset1:90
	ds_read2_b32 v[18:19], v28 offset0:115 offset1:123
	ds_read2_b32 v[20:21], v28 offset0:148 offset1:156
	ds_read2_b32 v[22:23], v28 offset0:181 offset1:189
	ds_read2_b32 v[24:25], v28 offset0:214 offset1:222
	ds_read2_b32 v[26:27], v28 offset0:247 offset1:255
	v_addc_co_u32_e32 v11, vcc, 0, v9, vcc
	global_store_dwordx4 v[10:11], v[4:7], off
	v_add_co_u32_e32 v10, vcc, s60, v8
	s_waitcnt lgkmcnt(6)
	v_cvt_pk_bf16_f32 v4, v14, v12
	v_addc_co_u32_e32 v11, vcc, 0, v9, vcc
	s_waitcnt lgkmcnt(4)
	v_cvt_pk_bf16_f32 v5, v16, v18
	s_waitcnt lgkmcnt(2)
	v_cvt_pk_bf16_f32 v6, v20, v22
	s_waitcnt lgkmcnt(0)
	v_cvt_pk_bf16_f32 v7, v24, v26
	v_add_co_u32_e32 v8, vcc, 0xc000, v8
	global_store_dwordx4 v[10:11], v[4:7], off
	s_nop 0
	v_addc_co_u32_e32 v9, vcc, 0, v9, vcc
	v_cvt_pk_bf16_f32 v4, v15, v13
	v_cvt_pk_bf16_f32 v5, v17, v19
	v_cvt_pk_bf16_f32 v6, v21, v23
	v_cvt_pk_bf16_f32 v7, v25, v27
	global_store_dwordx4 v[8:9], v[4:7], off
	s_waitcnt lgkmcnt(0)

; #define LAS __attribute__((address_space(3)))
; __device__ __forceinline__ unsigned pk2(float lo, float hi) { f32x2 v = {lo, hi}; bf16x2_t b = __builtin_convertvector(v, bf16x2_t); return __builtin_bit_cast(unsigned, b); }
; __device__ __forceinline__ void tr_item(const float* W, int K, int N, bf16_t* WT, int ldt, int rowmode, const float* ksc, LAS float* scr, int item, int lane) {
;     const int nblk = N / 32, kb = item / nblk, nb = item % nblk, k0 = 64 * kb, n0 = 32 * nb;
; #pragma unroll 16
;     for (int i = 0; i < 32; ++i) { const int kk = 2 * i + (lane >> 5); float v = W[(size_t)(k0 + kk) * N + n0 + (lane & 31)]; if (ksc) v *= ksc[k0 + kk]; scr[kk * 33 + (lane & 31)] = v; }
;     asm volatile("s_waitcnt lgkmcnt(0)" ::: "memory");
;     const int c = lane & 7;
; #pragma unroll
;     for (int j = 0; j < 4; ++j) { const int n = n0 + (lane >> 3) + 8 * j; const LAS float* s = scr + (8 * c) * 33 + (lane >> 3) + 8 * j;
;         u32x4 o; o.x = pk2(s[0 * 33], s[1 * 33]); o.y = pk2(s[2 * 33], s[3 * 33]); o.z = pk2(s[4 * 33], s[5 * 33]); o.w = pk2(s[6 * 33], s[7 * 33]);
;         int row = n; if (rowmode) row = (n >> 7) * 256 + (n & 127) + (rowmode == 2 ? 128 : 0);
;         *(u32x4*)(WT + (size_t)row * ldt + k0 + 8 * c) = o; }
;     asm volatile("s_waitcnt lgkmcnt(0)" ::: "memory");
.LBB0_123:
	global_load_dword v100, v[10:11], off
	v_add_u32_e32 v15, s9, v14
	v_add_u32_e32 v16, 6, v15
	v_mad_i64_i32 v[16:17], s[10:11], v16, s64, v[4:5]
	s_add_i32 s9, s9, 32
	v_lshl_add_u64 v[10:11], v[10:11], 0, s[16:17]
	s_cmp_lg_u32 s9, 64
	global_load_dword v101, v[8:9], off
	v_lshl_add_u64 v[8:9], v[8:9], 0, s[16:17]
	global_load_dword v102, v[6:7], off
	v_lshl_add_u64 v[6:7], v[6:7], 0, s[16:17]
	global_load_dword v103, v[16:17], off
	v_add_u32_e32 v16, 8, v15
	v_mad_i64_i32 v[16:17], s[10:11], v16, s64, v[4:5]
	global_load_dword v104, v[16:17], off
	v_add_u32_e32 v16, 10, v15
	v_mad_i64_i32 v[16:17], s[10:11], v16, s64, v[4:5]
	global_load_dword v105, v[16:17], off
	v_add_u32_e32 v16, 12, v15
	v_mad_i64_i32 v[16:17], s[10:11], v16, s64, v[4:5]
	global_load_dword v106, v[16:17], off
	v_add_u32_e32 v16, 14, v15
	v_mad_i64_i32 v[16:17], s[10:11], v16, s64, v[4:5]
	global_load_dword v107, v[16:17], off
	v_add_u32_e32 v16, 16, v15
	v_mad_i64_i32 v[16:17], s[10:11], v16, s64, v[4:5]
	global_load_dword v108, v[16:17], off
	v_add_u32_e32 v16, 18, v15
	v_mad_i64_i32 v[16:17], s[10:11], v16, s64, v[4:5]
	global_load_dword v109, v[16:17], off
	v_add_u32_e32 v16, 20, v15
	v_mad_i64_i32 v[16:17], s[10:11], v16, s64, v[4:5]
	global_load_dword v110, v[16:17], off
	v_add_u32_e32 v16, 22, v15
	v_mad_i64_i32 v[16:17], s[10:11], v16, s64, v[4:5]
	global_load_dword v111, v[16:17], off
	v_add_u32_e32 v16, 24, v15
	v_mad_i64_i32 v[16:17], s[10:11], v16, s64, v[4:5]
	global_load_dword v112, v[16:17], off
	v_add_u32_e32 v16, 26, v15
	v_mad_i64_i32 v[16:17], s[10:11], v16, s64, v[4:5]
	global_load_dword v113, v[16:17], off
	v_add_u32_e32 v16, 28, v15
	v_mad_i64_i32 v[16:17], s[10:11], v16, s64, v[4:5]
	v_add_u32_e32 v15, 30, v15
	global_load_dword v114, v[16:17], off
	v_mad_i64_i32 v[16:17], s[10:11], v15, s64, v[4:5]
	global_load_dword v115, v[16:17], off
	s_waitcnt vmcnt(15)
	ds_write_b32 v13, v100
	s_waitcnt vmcnt(14)
	ds_write_b32 v13, v101 offset:264
	s_waitcnt vmcnt(13)
	ds_write_b32 v13, v102 offset:528
	s_waitcnt vmcnt(12)
	ds_write_b32 v13, v103 offset:792
	s_waitcnt vmcnt(11)
	ds_write_b32 v13, v104 offset:1056
	s_waitcnt vmcnt(10)
	ds_write_b32 v13, v105 offset:1320
	s_waitcnt vmcnt(9)
	ds_write_b32 v13, v106 offset:1584
	s_waitcnt vmcnt(8)
	ds_write_b32 v13, v107 offset:1848
	s_waitcnt vmcnt(7)
	ds_write_b32 v13, v108 offset:2112
	s_waitcnt vmcnt(6)
	ds_write_b32 v13, v109 offset:2376
	s_waitcnt vmcnt(5)
	ds_write_b32 v13, v110 offset:2640
	s_waitcnt vmcnt(4)
	ds_write_b32 v13, v111 offset:2904
	s_waitcnt vmcnt(3)
	ds_write_b32 v13, v112 offset:3168
	s_waitcnt vmcnt(2)
	ds_write_b32 v13, v113 offset:3432
	s_waitcnt vmcnt(1)
	ds_write_b32 v13, v114 offset:3696
	s_waitcnt vmcnt(0)
	ds_write_b32 v13, v115 offset:3960
	v_add_u32_e32 v13, 0x1080, v13
	s_cbranch_scc1 .LBB0_123
	v_lshlrev_b32_e32 v4, 3, v12
	v_ashrrev_i32_e32 v2, 3, v12
	v_and_b32_e32 v4, 56, v4
	v_add_u32_e32 v8, s8, v2
	v_mul_u32_u24_e32 v5, 0x84, v4
	v_lshlrev_b32_e32 v2, 2, v2
	s_waitcnt lgkmcnt(0)
	v_add3_u32 v28, s3, v5, v2
	ds_read2_b32 v[10:11], v28 offset0:33 offset1:41
	ds_read2_b32 v[12:13], v28 offset1:8
	ds_read2_b32 v[14:15], v28 offset0:66 offset1:74
	ds_read2_b32 v[16:17], v28 offset0:99 offset1:107
	ds_read2_b32 v[18:19], v28 offset0:132 offset1:140
	ds_read2_b32 v[20:21], v28 offset0:165 offset1:173
	ds_read2_b32 v[22:23], v28 offset0:198 offset1:206
	ds_read2_b32 v[24:25], v28 offset0:231 offset1:239
	s_lshl_b64 s[4:5], s[4:5], 1
	s_add_u32 s4, s23, s4
	s_addc_u32 s5, s24, s5
	v_lshlrev_b32_e32 v2, 1, v4
	v_ashrrev_i32_e32 v9, 31, v8
	v_lshl_add_u64 v[26:27], s[4:5], 0, v[2:3]
	v_lshlrev_b64 v[8:9], 11, v[8:9]
	s_waitcnt lgkmcnt(6)
	v_cvt_pk_bf16_f32 v4, v12, v10
	s_waitcnt lgkmcnt(4)
	v_cvt_pk_bf16_f32 v5, v14, v16
	s_waitcnt lgkmcnt(2)
	v_cvt_pk_bf16_f32 v6, v18, v20
	s_waitcnt lgkmcnt(0)
	v_cvt_pk_bf16_f32 v7, v22, v24
	v_lshl_add_u64 v[8:9], v[26:27], 0, v[8:9]
	global_store_dwordx4 v[8:9], v[4:7], off
	v_add_co_u32_e32 v10, vcc, s59, v8
	s_nop 0
	v_cvt_pk_bf16_f32 v4, v13, v11
	v_cvt_pk_bf16_f32 v5, v15, v17
	v_cvt_pk_bf16_f32 v6, v19, v21
	v_cvt_pk_bf16_f32 v7, v23, v25
	ds_read2_b32 v[12:13], v28 offset0:49 offset1:57
	ds_read2_b32 v[14:15], v28 offset0:16 offset1:24
	ds_read2_b32 v[16:17], v28 offset0:82 offset1:90
	ds_read2_b32 v[18:19], v28 offset0:115 offset1:123
	ds_read2_b32 v[20:21], v28 offset0:148 offset1:156
	ds_read2_b32 v[22:23], v28 offset0:181 offset1:189
	ds_read2_b32 v[24:25], v28 offset0:214 offset1:222
	ds_read2_b32 v[26:27], v28 offset0:247 offset1:255
	v_addc_co_u32_e32 v11, vcc, 0, v9, vcc
	global_store_dwordx4 v[10:11], v[4:7], off
	v_add_co_u32_e32 v10, vcc, s60, v8
	s_waitcnt lgkmcnt(6)
	v_cvt_pk_bf16_f32 v4, v14, v12
	v_addc_co_u32_e32 v11, vcc, 0, v9, vcc
	s_waitcnt lgkmcnt(4)
	v_cvt_pk_bf16_f32 v5, v16, v18
	s_waitcnt lgkmcnt(2)
	v_cvt_pk_bf16_f32 v6, v20, v22
	s_waitcnt lgkmcnt(0)
	v_cvt_pk_bf16_f32 v7, v24, v26
	v_add_co_u32_e32 v8, vcc, 0xc000, v8
	global_store_dwordx4 v[10:11], v[4:7], off
	s_nop 0
	v_addc_co_u32_e32 v9, vcc, 0, v9, vcc
	v_cvt_pk_bf16_f32 v4, v15, v13
	v_cvt_pk_bf16_f32 v5, v17, v19
	v_cvt_pk_bf16_f32 v6, v21, v23
	v_cvt_pk_bf16_f32 v7, v25, v27
	global_store_dwordx4 v[8:9], v[4:7], off
	s_waitcnt lgkmcnt(0)
	s_branch .LBB0_16
